# GEMM phase prologues: all seven staging groups issued before the first counted wait (vmcnt 2 -> 8), barrier moved after them
# speedup vs baseline: 1.0065x; 1.0017x over previous
; #define PG8_STAGE(bufoff, gbase, voff) do { _Pragma("unroll") for (int _i = 0; _i < 2; ++_i) \
;         __builtin_amdgcn_global_load_lds((const unsigned*)((const char*)(gbase) + (voff)[_i]), (LAS unsigned*)(lds + (bufoff) + ldsw + _i * 8192), 16, 0, 0); } while (0)
; #define PG8_WAIT_V(n) asm volatile("s_waitcnt vmcnt(" #n ")" ::: "memory")
; #define PG8_BAR __builtin_amdgcn_s_barrier()
;     ...
;     for (int i = 0; i < 2; ++i) { int R, C; stage_rc(tid * 16 + i * 8192, R, C); const int Rb = Epi::PERM ? ((R & ~31) + perm32(R & 31)) : R;
;         voffA[i] = (unsigned)(R * g.lda + C) * 2u; voffB[i] = (unsigned)(Rb * K + C) * 2u; }
;     const size_t kstep = (size_t)(BK * 2);
;     const size_t hstepA = (size_t)HALF * g.lda * 2, hstepB = (size_t)HALF * K * 2;
;     const size_t tstepA = 2 * hstepA, tstepB = 2 * hstepB;
;     const unsigned ldsw = (unsigned)wid * 1024u;
;     const int aoff = lds_byte(wr * 64 + fr, fq * 8), boff = lds_byte(wc * 32 + fr, fq * 8);
;     ...
;         PG8_STAGE(PG8_SB(0, 0), cB, voffB); PG8_STAGE(PG8_SB(0, 1), cB + hstepB, voffB); PG8_STAGE(PG8_SA(0, 0), cA, voffA); PG8_STAGE(PG8_SA(0, 1), cA + hstepA, voffA);
;         if (wr == 1) PG8_BAR;
;         PG8_WAIT_V(2); PG8_BAR;
;         PG8_STAGE(PG8_SB(1, 0), cB + kstep, voffB); PG8_STAGE(PG8_SA(1, 0), cA + kstep, voffA); PG8_STAGE(PG8_SB(1, 1), cB + hstepB + kstep, voffB);
;         PG8_WAIT_V(6); PG8_BAR;
.LBB0_69:
	s_mov_b64 s[10:11], 0x80
	s_add_i32 m0, s29, 0x18000
	v_lshl_add_u64 v[0:1], v[0:1], 0, s[10:11]
	global_load_lds_dwordx4 v[0:1], off
	v_lshl_add_u64 v[0:1], v[2:3], 0, s[10:11]
	s_add_i32 m0, s29, 0x1a000
	s_add_i32 s35, s29, 0x8000
	global_load_lds_dwordx4 v[0:1], off
	v_lshl_add_u64 v[0:1], v[8:9], 0, s[10:11]
	s_mov_b32 m0, s35
	s_add_i32 s40, s29, 0xa000
	global_load_lds_dwordx4 v[0:1], off
	v_lshl_add_u64 v[0:1], v[10:11], 0, s[10:11]
	s_mov_b32 m0, s40
	s_lshr_b32 s3, s3, 26
	global_load_lds_dwordx4 v[0:1], off
	s_add_i32 m0, s29, 0x1c000
	v_lshl_add_u64 v[0:1], v[4:5], 0, s[10:11]
	global_load_lds_dwordx4 v[0:1], off
	v_lshl_add_u64 v[0:1], v[6:7], 0, s[10:11]
	s_add_i32 m0, s29, 0x1e000
	s_add_i32 s3, s2, s3
	global_load_lds_dwordx4 v[0:1], off
	s_waitcnt vmcnt(8)
	s_barrier
	v_bfe_u32 v1, v12, 4, 2
	v_and_b32_e32 v0, 15, v12
	v_lshlrev_b32_e32 v2, 4, v1
	v_lshl_or_b32 v137, s8, 6, v0
	v_lshl_or_b32 v0, v0, 6, v2
	v_lshlrev_b32_e32 v2, 2, v12
	s_and_b32 s41, s7, 3
	s_ashr_i32 s42, s3, 6
	s_lshl_b32 s3, s8, 13
	v_and_b32_e32 v2, 32, v2
	v_bitop3_b32 v3, v0, s3, v2 bitop3:0xde
	s_lshl_b32 s43, s41, 5
	s_lshl_b32 s3, s41, 12
	s_cmp_gt_i32 s2, 63
	s_cselect_b64 s[24:25], -1, 0
	s_add_i32 s44, s42, -2
	s_cmpk_lt_u32 s6, 0x100
	s_movk_i32 s6, 0xb00
	v_lshlrev_b32_e32 v136, 3, v1
	v_bitop3_b32 v158, v0, s3, v2 bitop3:0xde
	v_cmp_eq_u32_e64 s[10:11], 0, v1
	v_lshrrev_b32_e32 v1, 1, v13
	v_mul_lo_u32 v0, v15, s6
	s_mov_b32 s7, 0xb000
	v_mad_u64_u32 v[0:1], s[2:3], v1, s7, v[0:1]
	v_or_b32_e32 v0, v0, v14
	v_add_lshl_u32 v146, v0, v16, 1
	v_lshrrev_b32_e32 v1, 1, v17
	v_mul_lo_u32 v0, v19, s6
	v_mad_u64_u32 v[0:1], s[2:3], v1, s7, v[0:1]
	s_waitcnt vmcnt(6)
	s_mov_b64 s[8:9], 0xb0080
	v_or_b32_e32 v0, v0, v18
	v_lshl_add_u64 v[138:139], v[146:147], 0, s[8:9]
	v_add_lshl_u32 v146, v0, v20, 1
	s_cselect_b64 s[26:27], -1, 0
	s_mov_b32 s45, 0
	s_ashr_i32 s46, s36, 31
	s_ashr_i32 s47, s38, 31
	v_lshl_add_u64 v[140:141], v[146:147], 0, s[8:9]
	v_add_u32_e32 v159, 0, v3
	s_barrier
	s_branch .LBB0_72

; #define PG8_STAGE(bufoff, gbase, voff) do { _Pragma("unroll") for (int _i = 0; _i < 2; ++_i) \
;         __builtin_amdgcn_global_load_lds((const unsigned*)((const char*)(gbase) + (voff)[_i]), (LAS unsigned*)(lds + (bufoff) + ldsw + _i * 8192), 16, 0, 0); } while (0)
; #define PG8_WAIT_V(n) asm volatile("s_waitcnt vmcnt(" #n ")" ::: "memory")
; #define PG8_BAR __builtin_amdgcn_s_barrier()
;     ...
;     for (int i = 0; i < 2; ++i) { int R, C; stage_rc(tid * 16 + i * 8192, R, C); const int Rb = Epi::PERM ? ((R & ~31) + perm32(R & 31)) : R;
;         voffA[i] = (unsigned)(R * g.lda + C) * 2u; voffB[i] = (unsigned)(Rb * K + C) * 2u; }
;     const size_t kstep = (size_t)(BK * 2);
;     const size_t hstepA = (size_t)HALF * g.lda * 2, hstepB = (size_t)HALF * K * 2;
;     const size_t tstepA = 2 * hstepA, tstepB = 2 * hstepB;
;     const unsigned ldsw = (unsigned)wid * 1024u;
;     const int aoff = lds_byte(wr * 64 + fr, fq * 8), boff = lds_byte(wc * 32 + fr, fq * 8);
;     ...
;         PG8_STAGE(PG8_SB(0, 0), cB, voffB); PG8_STAGE(PG8_SB(0, 1), cB + hstepB, voffB); PG8_STAGE(PG8_SA(0, 0), cA, voffA); PG8_STAGE(PG8_SA(0, 1), cA + hstepA, voffA);
;         if (wr == 1) PG8_BAR;
;         PG8_WAIT_V(2); PG8_BAR;
;         PG8_STAGE(PG8_SB(1, 0), cB + kstep, voffB); PG8_STAGE(PG8_SA(1, 0), cA + kstep, voffA); PG8_STAGE(PG8_SB(1, 1), cB + hstepB + kstep, voffB);
;         PG8_WAIT_V(6); PG8_BAR;
.LBB0_118:
	s_mov_b64 s[10:11], 0x80
	s_add_i32 m0, s41, 0x18000
	v_lshl_add_u64 v[0:1], v[0:1], 0, s[10:11]
	global_load_lds_dwordx4 v[0:1], off
	v_lshl_add_u64 v[0:1], v[2:3], 0, s[10:11]
	s_add_i32 m0, s41, 0x1a000
	s_add_i32 s45, s41, 0x8000
	global_load_lds_dwordx4 v[0:1], off
	v_lshl_add_u64 v[0:1], v[8:9], 0, s[10:11]
	s_mov_b32 m0, s45
	s_add_i32 s46, s41, 0xa000
	global_load_lds_dwordx4 v[0:1], off
	v_lshl_add_u64 v[0:1], v[10:11], 0, s[10:11]
	s_mov_b32 m0, s46
	v_bfe_u32 v2, v12, 4, 2
	global_load_lds_dwordx4 v[0:1], off
	s_add_i32 m0, s41, 0x1c000
	v_lshl_add_u64 v[0:1], v[4:5], 0, s[10:11]
	global_load_lds_dwordx4 v[0:1], off
	v_lshl_add_u64 v[0:1], v[6:7], 0, s[10:11]
	s_add_i32 m0, s41, 0x1e000
	s_lshr_b32 s5, s5, 26
	global_load_lds_dwordx4 v[0:1], off
	s_waitcnt vmcnt(8)
	s_barrier
	v_and_b32_e32 v1, 15, v12
	v_lshl_or_b32 v206, s9, 6, v1
	s_add_i32 s5, s4, s5
	v_lshlrev_b32_e32 v146, 4, v2
	v_lshlrev_b32_e32 v207, 2, v206
	s_and_b32 s8, s8, 3
	s_ashr_i32 s47, s5, 6
	v_lshl_or_b32 v1, v1, 6, v146
	s_lshl_b32 s5, s9, 13
	v_and_b32_e32 v3, 32, v207
	v_bitop3_b32 v4, v1, s5, v3 bitop3:0xde
	s_lshl_b32 s9, s8, 5
	s_lshl_b32 s5, s8, 12
	s_cmp_gt_i32 s4, 63
	s_cselect_b64 s[28:29], -1, 0
	s_add_i32 s48, s47, -2
	s_cmpk_lt_u32 s7, 0x100
	v_lshlrev_b32_e32 v3, 2, v12
	s_cselect_b64 s[30:31], -1, 0
	s_lshl_b32 s4, s8, 6
	v_readlane_b32 s10, v254, 28
	v_and_b32_e32 v3, 32, v3
	v_readlane_b32 s11, v254, 29
	s_add_u32 s4, s10, s4
	v_bitop3_b32 v208, v1, s5, v3 bitop3:0xde
	s_addc_u32 s5, s11, 0
	v_lshl_add_u64 v[164:165], s[4:5], 0, v[146:147]
	v_lshlrev_b32_e32 v1, 4, v206
	v_readlane_b32 s4, v254, 2
	s_lshl_b32 s7, s8, 2
	v_lshlrev_b32_e32 v146, 2, v144
	v_add_u32_e32 v5, s4, v1
	v_readlane_b32 s4, v254, 3
	v_lshlrev_b32_e32 v0, 3, v2
	v_cmp_eq_u32_e64 s[10:11], 0, v2
	v_add_u32_e32 v6, s4, v1
	v_readlane_b32 s4, v254, 4
	s_movk_i32 s8, 0xb00
	s_mov_b32 s12, 0xb000
	v_add_u32_e32 v7, s4, v1
	v_readlane_b32 s4, v254, 5
	s_waitcnt vmcnt(6)
	s_mov_b64 s[14:15], 0xb0080
	s_mov_b32 s49, 0
	v_add_u32_e32 v8, s4, v1
	v_readlane_b32 s4, v254, 6
	v_or_b32_e32 v209, s9, v0
	v_add_u32_e32 v210, 0, v4
	v_add_u32_e32 v9, s4, v1
	v_readlane_b32 s4, v254, 7
	v_add_u32_e32 v211, s7, v5
	v_add_u32_e32 v227, s7, v6
	v_add_u32_e32 v10, s4, v1
	v_readlane_b32 s4, v254, 8
	v_add_u32_e32 v145, s7, v7
	v_add_u32_e32 v214, s7, v8
	v_add_u32_e32 v11, s4, v1
	v_readlane_b32 s4, v254, 9
	v_add_u32_e32 v215, s7, v9
	v_add_u32_e32 v216, s7, v10
	v_add_u32_e32 v1, s4, v1
	v_readlane_b32 s4, v254, 25
	v_readlane_b32 s5, v254, 26
	s_add_u32 s50, s4, 0x1e846000
	s_addc_u32 s51, s5, 0
	v_lshl_add_u64 v[2:3], s[4:5], 0, v[146:147]
	s_mov_b64 s[4:5], 0x1e868000
	v_lshl_add_u64 v[166:167], v[2:3], 0, s[4:5]
	v_lshrrev_b32_e32 v3, 1, v13
	v_mul_lo_u32 v2, v15, s8
	v_mad_u64_u32 v[2:3], s[4:5], v3, s12, v[2:3]
	v_or_b32_e32 v2, v2, v14
	v_add_lshl_u32 v146, v2, v16, 1
	v_lshrrev_b32_e32 v3, 1, v17
	v_mul_lo_u32 v2, v19, s8
	v_mad_u64_u32 v[2:3], s[4:5], v3, s12, v[2:3]
	v_or_b32_e32 v2, v2, v18
	v_lshl_add_u64 v[168:169], v[146:147], 0, s[14:15]
	v_add_lshl_u32 v146, v2, v20, 1
	s_ashr_i32 s52, s36, 31
	s_ashr_i32 s53, s38, 31
	v_lshl_add_u64 v[170:171], v[146:147], 0, s[14:15]
	v_add_u32_e32 v217, s7, v11
	v_add_u32_e32 v218, s7, v1
	s_lshl_b32 s54, s9, 2
	v_lshlrev_b32_e32 v146, 2, v0
	s_barrier
	s_branch .LBB0_121

; #define LAS __attribute__((address_space(3)))
; #define PG8_STAGE(bufoff, gbase, voff) do { _Pragma("unroll") for (int _i = 0; _i < 2; ++_i) \
;         __builtin_amdgcn_global_load_lds((const unsigned*)((const char*)(gbase) + (voff)[_i]), (LAS unsigned*)(lds + (bufoff) + ldsw + _i * 8192), 16, 0, 0); } while (0)
; #define PG8_WAIT_V(n) asm volatile("s_waitcnt vmcnt(" #n ")" ::: "memory")
; #define PG8_BAR __builtin_amdgcn_s_barrier()
;     ...
;     for (int i = 0; i < 2; ++i) { int R, C; stage_rc(tid * 16 + i * 8192, R, C); const int Rb = Epi::PERM ? ((R & ~31) + perm32(R & 31)) : R;
;         voffA[i] = (unsigned)(R * g.lda + C) * 2u; voffB[i] = (unsigned)(Rb * K + C) * 2u; }
;     const size_t kstep = (size_t)(BK * 2);
;     const size_t hstepA = (size_t)HALF * g.lda * 2, hstepB = (size_t)HALF * K * 2;
;     const size_t tstepA = 2 * hstepA, tstepB = 2 * hstepB;
;     const unsigned ldsw = (unsigned)wid * 1024u;
;     const int aoff = lds_byte(wr * 64 + fr, fq * 8), boff = lds_byte(wc * 32 + fr, fq * 8);
;     ...
;         PG8_STAGE(PG8_SB(0, 0), cB, voffB); PG8_STAGE(PG8_SB(0, 1), cB + hstepB, voffB); PG8_STAGE(PG8_SA(0, 0), cA, voffA); PG8_STAGE(PG8_SA(0, 1), cA + hstepA, voffA);
;         if (wr == 1) PG8_BAR;
;         PG8_WAIT_V(2); PG8_BAR;
;         PG8_STAGE(PG8_SB(1, 0), cB + kstep, voffB); PG8_STAGE(PG8_SA(1, 0), cA + kstep, voffA); PG8_STAGE(PG8_SB(1, 1), cB + hstepB + kstep, voffB);
;         PG8_WAIT_V(6); PG8_BAR;
;     ...
;         if constexpr (Epi::NEEDS_RS) { if (wid < 4) __builtin_amdgcn_global_load_lds((const unsigned*)(E.rsv + cur.pm * 256 + wid * 64 + lane), (LAS unsigned*)(lds + rsoff + wid * 256), 4, 0, 0); }
.LBB0_195:
	s_mov_b64 s[16:17], 0x80
	s_add_i32 m0, s25, 0x18000
	v_lshl_add_u64 v[0:1], v[0:1], 0, s[16:17]
	global_load_lds_dwordx4 v[0:1], off
	v_lshl_add_u64 v[0:1], v[2:3], 0, s[16:17]
	s_add_i32 m0, s25, 0x1a000
	s_add_i32 s42, s25, 0x8000
	global_load_lds_dwordx4 v[0:1], off
	v_lshl_add_u64 v[0:1], v[8:9], 0, s[16:17]
	s_mov_b32 m0, s42
	s_add_i32 s43, s25, 0xa000
	global_load_lds_dwordx4 v[0:1], off
	v_lshl_add_u64 v[0:1], v[10:11], 0, s[16:17]
	s_mov_b32 m0, s43
	s_sext_i32_i16 s50, s6
	global_load_lds_dwordx4 v[0:1], off
	s_add_i32 m0, s25, 0x1c000
	v_lshl_add_u64 v[0:1], v[4:5], 0, s[16:17]
	global_load_lds_dwordx4 v[0:1], off
	v_lshl_add_u64 v[0:1], v[6:7], 0, s[16:17]
	s_add_i32 m0, s25, 0x1e000
	v_and_b32_e32 v2, 15, v15
	global_load_lds_dwordx4 v[0:1], off
	s_waitcnt vmcnt(8)
	s_barrier
	v_lshrrev_b32_e32 v0, 1, v15
	v_and_b32_e32 v0, 24, v0
	s_lshr_b32 s6, s9, 26
	v_lshlrev_b32_e32 v3, 1, v0
	s_add_i32 s6, s8, s6
	v_lshl_or_b32 v142, s14, 6, v2
	v_lshl_or_b32 v3, v2, 6, v3
	v_lshlrev_b32_e32 v2, 2, v2
	s_ashr_i32 s44, s6, 6
	s_lshl_b32 s6, s14, 13
	v_and_b32_e32 v4, 32, v2
	v_bitop3_b32 v5, v3, s6, v4 bitop3:0xde
	s_lshl_b32 s6, s13, 5
	s_and_b32 s16, s6, 0x60
	s_lshl_b32 s6, s16, 7
	s_cmp_lt_i32 s13, 4
	v_bitop3_b32 v143, v3, s6, v4 bitop3:0xde
	s_cselect_b64 s[6:7], -1, 0
	s_cmp_gt_i32 s8, 63
	s_cselect_b64 s[8:9], -1, 0
	s_lshl_b32 s14, s14, 8
	v_and_b32_e32 v1, 63, v15
	s_add_i32 s14, s14, 0
	v_add_u32_e32 v156, s14, v2
	s_and_b32 s14, s12, 0xffffffc0
	v_lshlrev_b32_e32 v146, 2, v1
	v_lshlrev_b32_e32 v1, 14, v17
	s_ashr_i32 s15, s14, 31
	v_and_b32_e32 v1, 0xffff8000, v1
	s_lshl_b64 s[14:15], s[14:15], 2
	v_lshl_add_u32 v1, v16, 11, v1
	v_and_b32_e32 v2, 1, v17
	s_add_u32 s10, s10, s14
	v_lshl_or_b32 v1, v2, 6, v1
	s_addc_u32 s11, s11, s15
	v_lshl_add_u32 v138, v18, 1, v1
	v_lshlrev_b32_e32 v1, 14, v12
	v_lshl_add_u64 v[136:137], s[10:11], 0, v[146:147]
	s_lshl_b32 s10, s13, 8
	v_and_b32_e32 v1, 0xffff8000, v1
	s_waitcnt vmcnt(6)
	s_add_i32 s45, s10, 0
	s_add_i32 s46, s44, -2
	v_lshl_add_u32 v1, v13, 11, v1
	v_and_b32_e32 v2, 1, v12
	s_cmpk_lt_u32 s12, 0x100
	v_lshl_or_b32 v1, v2, 6, v1
	s_cselect_b64 s[14:15], -1, 0
	s_ashr_i32 s47, s31, 31
	v_mov_b32_e32 v139, v147
	v_lshl_add_u32 v140, v14, 1, v1
	v_mov_b32_e32 v141, v147
	s_mov_b32 s17, 0
	v_add_u32_e32 v157, 0, v5
	s_lshl_b32 s68, s16, 1
	v_lshlrev_b32_e32 v146, 1, v0
	s_barrier
	s_branch .LBB0_198

; #define PG8_STAGE(bufoff, gbase, voff) do { _Pragma("unroll") for (int _i = 0; _i < 2; ++_i) \
;         __builtin_amdgcn_global_load_lds((const unsigned*)((const char*)(gbase) + (voff)[_i]), (LAS unsigned*)(lds + (bufoff) + ldsw + _i * 8192), 16, 0, 0); } while (0)
; #define PG8_WAIT_V(n) asm volatile("s_waitcnt vmcnt(" #n ")" ::: "memory")
; #define PG8_BAR __builtin_amdgcn_s_barrier()
;     ...
;     for (int i = 0; i < 2; ++i) { int R, C; stage_rc(tid * 16 + i * 8192, R, C); const int Rb = Epi::PERM ? ((R & ~31) + perm32(R & 31)) : R;
;         voffA[i] = (unsigned)(R * g.lda + C) * 2u; voffB[i] = (unsigned)(Rb * K + C) * 2u; }
;     const size_t kstep = (size_t)(BK * 2);
;     const size_t hstepA = (size_t)HALF * g.lda * 2, hstepB = (size_t)HALF * K * 2;
;     const size_t tstepA = 2 * hstepA, tstepB = 2 * hstepB;
;     const unsigned ldsw = (unsigned)wid * 1024u;
;     const int aoff = lds_byte(wr * 64 + fr, fq * 8), boff = lds_byte(wc * 32 + fr, fq * 8);
;     ...
;         PG8_STAGE(PG8_SB(0, 0), cB, voffB); PG8_STAGE(PG8_SB(0, 1), cB + hstepB, voffB); PG8_STAGE(PG8_SA(0, 0), cA, voffA); PG8_STAGE(PG8_SA(0, 1), cA + hstepA, voffA);
;         if (wr == 1) PG8_BAR;
;         PG8_WAIT_V(2); PG8_BAR;
;         PG8_STAGE(PG8_SB(1, 0), cB + kstep, voffB); PG8_STAGE(PG8_SA(1, 0), cA + kstep, voffA); PG8_STAGE(PG8_SB(1, 1), cB + hstepB + kstep, voffB);
;         PG8_WAIT_V(6); PG8_BAR;
.LBB0_224:
	s_mov_b64 s[10:11], 0x80
	s_add_i32 m0, s35, 0x18000
	v_lshl_add_u64 v[0:1], v[0:1], 0, s[10:11]
	global_load_lds_dwordx4 v[0:1], off
	v_lshl_add_u64 v[0:1], v[2:3], 0, s[10:11]
	s_add_i32 m0, s35, 0x1a000
	s_add_i32 s39, s35, 0x8000
	global_load_lds_dwordx4 v[0:1], off
	v_lshl_add_u64 v[0:1], v[8:9], 0, s[10:11]
	s_mov_b32 m0, s39
	s_add_i32 s40, s35, 0xa000
	global_load_lds_dwordx4 v[0:1], off
	v_lshl_add_u64 v[0:1], v[10:11], 0, s[10:11]
	s_mov_b32 m0, s40
	s_lshr_b32 s3, s3, 26
	global_load_lds_dwordx4 v[0:1], off
	s_add_i32 m0, s35, 0x1c000
	v_lshl_add_u64 v[0:1], v[4:5], 0, s[10:11]
	global_load_lds_dwordx4 v[0:1], off
	v_lshl_add_u64 v[0:1], v[6:7], 0, s[10:11]
	s_add_i32 m0, s35, 0x1e000
	s_add_i32 s3, s2, s3
	global_load_lds_dwordx4 v[0:1], off
	s_waitcnt vmcnt(8)
	s_barrier
	v_bfe_u32 v1, v12, 4, 2
	v_and_b32_e32 v0, 15, v12
	v_lshlrev_b32_e32 v2, 4, v1
	v_lshl_or_b32 v137, s8, 6, v0
	v_lshl_or_b32 v0, v0, 6, v2
	v_lshlrev_b32_e32 v2, 2, v12
	s_and_b32 s41, s7, 3
	s_ashr_i32 s42, s3, 6
	s_lshl_b32 s3, s8, 13
	v_and_b32_e32 v2, 32, v2
	v_bitop3_b32 v3, v0, s3, v2 bitop3:0xde
	s_lshl_b32 s43, s41, 5
	s_lshl_b32 s3, s41, 12
	s_cmp_gt_i32 s2, 63
	s_cselect_b64 s[24:25], -1, 0
	s_add_i32 s44, s42, -2
	s_movk_i32 s7, 0xe00
	v_lshlrev_b32_e32 v136, 3, v1
	v_bitop3_b32 v158, v0, s3, v2 bitop3:0xde
	s_cmpk_lt_u32 s6, 0x100
	v_cmp_eq_u32_e64 s[10:11], 0, v1
	v_lshrrev_b32_e32 v1, 1, v13
	v_mul_lo_u32 v0, v15, s7
	s_mov_b32 s6, 0xe000
	v_mad_u64_u32 v[0:1], s[2:3], v1, s6, v[0:1]
	v_or_b32_e32 v0, v0, v14
	v_add_lshl_u32 v146, v0, v16, 1
	v_lshrrev_b32_e32 v1, 1, v17
	v_mul_lo_u32 v0, v19, s7
	v_mad_u64_u32 v[0:1], s[2:3], v1, s6, v[0:1]
	s_waitcnt vmcnt(6)
	s_mov_b64 s[8:9], 0xe0080
	v_or_b32_e32 v0, v0, v18
	v_lshl_add_u64 v[138:139], v[146:147], 0, s[8:9]
	v_add_lshl_u32 v146, v0, v20, 1
	s_cselect_b64 s[26:27], -1, 0
	s_mov_b32 s45, 0
	s_ashr_i32 s46, s28, 31
	s_ashr_i32 s47, s29, 31
	v_lshl_add_u64 v[140:141], v[146:147], 0, s[8:9]
	v_add_u32_e32 v159, 0, v3
	s_barrier
	s_branch .LBB0_227

; #define PG8_STAGE(bufoff, gbase, voff) do { _Pragma("unroll") for (int _i = 0; _i < 2; ++_i) \
;         __builtin_amdgcn_global_load_lds((const unsigned*)((const char*)(gbase) + (voff)[_i]), (LAS unsigned*)(lds + (bufoff) + ldsw + _i * 8192), 16, 0, 0); } while (0)
; #define PG8_WAIT_V(n) asm volatile("s_waitcnt vmcnt(" #n ")" ::: "memory")
; #define PG8_BAR __builtin_amdgcn_s_barrier()
;     ...
;     for (int i = 0; i < 2; ++i) { int R, C; stage_rc(tid * 16 + i * 8192, R, C); const int Rb = Epi::PERM ? ((R & ~31) + perm32(R & 31)) : R;
;         voffA[i] = (unsigned)(R * g.lda + C) * 2u; voffB[i] = (unsigned)(Rb * K + C) * 2u; }
;     const size_t kstep = (size_t)(BK * 2);
;     const size_t hstepA = (size_t)HALF * g.lda * 2, hstepB = (size_t)HALF * K * 2;
;     const size_t tstepA = 2 * hstepA, tstepB = 2 * hstepB;
;     const unsigned ldsw = (unsigned)wid * 1024u;
;     const int aoff = lds_byte(wr * 64 + fr, fq * 8), boff = lds_byte(wc * 32 + fr, fq * 8);
;     ...
;         PG8_STAGE(PG8_SB(0, 0), cB, voffB); PG8_STAGE(PG8_SB(0, 1), cB + hstepB, voffB); PG8_STAGE(PG8_SA(0, 0), cA, voffA); PG8_STAGE(PG8_SA(0, 1), cA + hstepA, voffA);
;         if (wr == 1) PG8_BAR;
;         PG8_WAIT_V(2); PG8_BAR;
;         PG8_STAGE(PG8_SB(1, 0), cB + kstep, voffB); PG8_STAGE(PG8_SA(1, 0), cA + kstep, voffA); PG8_STAGE(PG8_SB(1, 1), cB + hstepB + kstep, voffB);
;         PG8_WAIT_V(6); PG8_BAR;
;     __device__ __forceinline__ void operator()(const f32x4 (&acc)[2][2][4][2], const Unit& u, int wr, int wc, int fr, int fq, const LAS float* rsl) const {
;     ...
;             const f32x4 p0 = *(const f32x4*)(pscale + col), p1 = *(const f32x4*)(pscale + col + 4);
.LBB0_272:
	s_lshl_b32 s14, s20, 10
	s_ashr_i32 s15, s14, 31
	s_lshl_b64 s[14:15], s[14:15], 2
	s_waitcnt lgkmcnt(0)
	s_add_u32 s2, s2, s14
	v_lshrrev_b32_e32 v20, 1, v18
	s_addc_u32 s3, s3, s15
	s_lshr_b32 s5, s5, 26
	v_and_b32_e32 v20, 24, v20
	v_and_b32_e32 v19, 15, v18
	s_add_i32 s5, s4, s5
	v_lshlrev_b32_e32 v21, 1, v20
	v_lshlrev_b32_e32 v18, 2, v18
	s_ashr_i32 s46, s5, 6
	v_lshl_or_b32 v166, s12, 6, v19
	v_lshl_or_b32 v19, v19, 6, v21
	s_lshl_b32 s5, s12, 13
	v_and_b32_e32 v18, 32, v18
	v_bitop3_b32 v21, v19, s5, v18 bitop3:0xde
	s_lshl_b32 s5, s13, 5
	s_mov_b64 s[12:13], 0x80
	s_add_i32 m0, s27, 0x18000
	v_lshl_add_u64 v[0:1], v[0:1], 0, s[12:13]
	global_load_lds_dwordx4 v[0:1], off
	v_lshl_add_u64 v[0:1], v[2:3], 0, s[12:13]
	s_add_i32 m0, s27, 0x1a000
	s_add_i32 s47, s27, 0x8000
	global_load_lds_dwordx4 v[0:1], off
	v_lshl_add_u64 v[0:1], v[8:9], 0, s[12:13]
	s_mov_b32 m0, s47
	s_add_i32 s48, s27, 0xa000
	global_load_lds_dwordx4 v[0:1], off
	v_lshl_add_u64 v[0:1], v[10:11], 0, s[12:13]
	s_mov_b32 m0, s48
	s_sext_i32_i8 s52, s10
	global_load_lds_dwordx4 v[0:1], off
	s_add_i32 m0, s27, 0x1c000
	v_lshl_add_u64 v[0:1], v[4:5], 0, s[12:13]
	global_load_lds_dwordx4 v[0:1], off
	v_lshl_add_u64 v[0:1], v[6:7], 0, s[12:13]
	s_add_i32 m0, s27, 0x1e000
	s_and_b32 s10, s5, 0x60
	global_load_lds_dwordx4 v[0:1], off
	s_waitcnt vmcnt(8)
	s_barrier
	v_lshlrev_b32_e32 v0, 13, v12
	v_and_b32_e32 v0, 0xffffc000, v0
	v_lshl_add_u32 v0, v13, 10, v0
	v_and_b32_e32 v1, 1, v12
	v_lshl_or_b32 v0, v1, 6, v0
	s_lshl_b32 s5, s10, 7
	v_lshl_add_u32 v142, v14, 1, v0
	v_lshlrev_b32_e32 v0, 13, v15
	s_cmp_gt_i32 s4, 63
	v_and_b32_e32 v0, 0xffffc000, v0
	v_bitop3_b32 v167, v19, s5, v18 bitop3:0xde
	s_waitcnt vmcnt(6)
	s_cselect_b64 s[4:5], -1, 0
	s_add_i32 s49, s46, -2
	v_lshl_add_u32 v0, v16, 10, v0
	v_and_b32_e32 v1, 1, v15
	s_cmpk_lt_u32 s11, 0x100
	v_lshl_or_b32 v0, v1, 6, v0
	s_cselect_b64 s[14:15], -1, 0
	s_ashr_i32 s50, s36, 31
	v_or_b32_e32 v168, s10, v20
	v_mov_b32_e32 v143, v147
	v_lshl_add_u32 v156, v17, 1, v0
	v_mov_b32_e32 v157, v147
	s_mov_b32 s51, 0
	v_add_u32_e32 v169, 0, v21
	s_barrier
	s_branch .LBB0_275

; #define PG8_STAGE(bufoff, gbase, voff) do { _Pragma("unroll") for (int _i = 0; _i < 2; ++_i) \
;         __builtin_amdgcn_global_load_lds((const unsigned*)((const char*)(gbase) + (voff)[_i]), (LAS unsigned*)(lds + (bufoff) + ldsw + _i * 8192), 16, 0, 0); } while (0)
; #define PG8_WAIT_V(n) asm volatile("s_waitcnt vmcnt(" #n ")" ::: "memory")
; #define PG8_BAR __builtin_amdgcn_s_barrier()
;     ...
;     for (int i = 0; i < 2; ++i) { int R, C; stage_rc(tid * 16 + i * 8192, R, C); const int Rb = Epi::PERM ? ((R & ~31) + perm32(R & 31)) : R;
;         voffA[i] = (unsigned)(R * g.lda + C) * 2u; voffB[i] = (unsigned)(Rb * K + C) * 2u; }
;     const size_t kstep = (size_t)(BK * 2);
;     const size_t hstepA = (size_t)HALF * g.lda * 2, hstepB = (size_t)HALF * K * 2;
;     const size_t tstepA = 2 * hstepA, tstepB = 2 * hstepB;
;     const unsigned ldsw = (unsigned)wid * 1024u;
;     const int aoff = lds_byte(wr * 64 + fr, fq * 8), boff = lds_byte(wc * 32 + fr, fq * 8);
;     ...
;         PG8_STAGE(PG8_SB(0, 0), cB, voffB); PG8_STAGE(PG8_SB(0, 1), cB + hstepB, voffB); PG8_STAGE(PG8_SA(0, 0), cA, voffA); PG8_STAGE(PG8_SA(0, 1), cA + hstepA, voffA);
;         if (wr == 1) PG8_BAR;
;         PG8_WAIT_V(2); PG8_BAR;
;         PG8_STAGE(PG8_SB(1, 0), cB + kstep, voffB); PG8_STAGE(PG8_SA(1, 0), cA + kstep, voffA); PG8_STAGE(PG8_SB(1, 1), cB + hstepB + kstep, voffB);
;         PG8_WAIT_V(6); PG8_BAR;
.LBB0_299:
	s_mov_b64 s[22:23], 0x80
	s_add_i32 m0, s35, 0x18000
	v_lshl_add_u64 v[0:1], v[0:1], 0, s[22:23]
	global_load_lds_dwordx4 v[0:1], off
	v_lshl_add_u64 v[0:1], v[2:3], 0, s[22:23]
	s_add_i32 m0, s35, 0x1a000
	s_add_i32 s39, s35, 0x8000
	global_load_lds_dwordx4 v[0:1], off
	v_lshl_add_u64 v[0:1], v[8:9], 0, s[22:23]
	s_mov_b32 m0, s39
	s_add_i32 s40, s35, 0xa000
	global_load_lds_dwordx4 v[0:1], off
	v_lshl_add_u64 v[0:1], v[10:11], 0, s[22:23]
	s_mov_b32 m0, s40
	s_lshr_b32 s5, s5, 26
	global_load_lds_dwordx4 v[0:1], off
	s_add_i32 m0, s35, 0x1c000
	v_lshl_add_u64 v[0:1], v[4:5], 0, s[22:23]
	global_load_lds_dwordx4 v[0:1], off
	v_lshl_add_u64 v[0:1], v[6:7], 0, s[22:23]
	s_add_i32 m0, s35, 0x1e000
	s_add_i32 s5, s4, s5
	global_load_lds_dwordx4 v[0:1], off
	s_waitcnt vmcnt(8)
	s_barrier
	v_lshrrev_b32_e32 v0, 1, v12
	v_and_b32_e32 v0, 24, v0
	v_and_b32_e32 v1, 15, v12
	v_lshlrev_b32_e32 v2, 1, v0
	v_lshl_or_b32 v142, s11, 6, v1
	v_lshl_or_b32 v1, v1, 6, v2
	v_lshlrev_b32_e32 v2, 2, v12
	s_sext_i32_i8 s47, s6
	s_ashr_i32 s6, s5, 6
	s_lshl_b32 s5, s11, 13
	v_and_b32_e32 v2, 32, v2
	v_bitop3_b32 v4, v1, s5, v2 bitop3:0xde
	s_lshl_b32 s5, s12, 5
	s_and_b32 s11, s5, 0x60
	s_lshl_b32 s5, s11, 7
	s_cmp_gt_i32 s4, 63
	s_cselect_b64 s[22:23], -1, 0
	s_add_i32 s41, s6, -2
	s_movk_i32 s12, 0xe00
	v_bitop3_b32 v143, v1, s5, v2 bitop3:0xde
	s_cmpk_lt_u32 s10, 0x100
	v_lshrrev_b32_e32 v1, 1, v13
	v_mul_lo_u32 v2, v15, s12
	s_mov_b32 s10, 0xe000
	v_mad_u64_u32 v[2:3], s[4:5], v1, s10, v[2:3]
	v_or_b32_e32 v1, v2, v14
	v_add_lshl_u32 v146, v1, v16, 1
	v_lshrrev_b32_e32 v1, 1, v17
	v_mul_lo_u32 v2, v19, s12
	v_mad_u64_u32 v[2:3], s[4:5], v1, s10, v[2:3]
	s_waitcnt vmcnt(6)
	s_mov_b64 s[26:27], 0xe0080
	v_or_b32_e32 v1, v2, v18
	v_lshl_add_u64 v[136:137], v[146:147], 0, s[26:27]
	v_add_lshl_u32 v146, v1, v20, 1
	s_cselect_b64 s[24:25], -1, 0
	s_ashr_i32 s42, s34, 31
	v_lshl_add_u64 v[138:139], v[146:147], 0, s[26:27]
	s_mov_b32 s43, 0
	v_add_u32_e32 v156, 0, v4
	s_lshl_b32 s68, s11, 1
	v_lshlrev_b32_e32 v146, 1, v0
	s_barrier
	s_branch .LBB0_302

; #define LAS __attribute__((address_space(3)))
; #define PG8_STAGE(bufoff, gbase, voff) do { _Pragma("unroll") for (int _i = 0; _i < 2; ++_i) \
;         __builtin_amdgcn_global_load_lds((const unsigned*)((const char*)(gbase) + (voff)[_i]), (LAS unsigned*)(lds + (bufoff) + ldsw + _i * 8192), 16, 0, 0); } while (0)
; #define PG8_WAIT_V(n) asm volatile("s_waitcnt vmcnt(" #n ")" ::: "memory")
; #define PG8_BAR __builtin_amdgcn_s_barrier()
;     ...
;     for (int i = 0; i < 2; ++i) { int R, C; stage_rc(tid * 16 + i * 8192, R, C); const int Rb = Epi::PERM ? ((R & ~31) + perm32(R & 31)) : R;
;         voffA[i] = (unsigned)(R * g.lda + C) * 2u; voffB[i] = (unsigned)(Rb * K + C) * 2u; }
;     const size_t kstep = (size_t)(BK * 2);
;     const size_t hstepA = (size_t)HALF * g.lda * 2, hstepB = (size_t)HALF * K * 2;
;     const size_t tstepA = 2 * hstepA, tstepB = 2 * hstepB;
;     const unsigned ldsw = (unsigned)wid * 1024u;
;     const int aoff = lds_byte(wr * 64 + fr, fq * 8), boff = lds_byte(wc * 32 + fr, fq * 8);
;     ...
;         PG8_STAGE(PG8_SB(0, 0), cB, voffB); PG8_STAGE(PG8_SB(0, 1), cB + hstepB, voffB); PG8_STAGE(PG8_SA(0, 0), cA, voffA); PG8_STAGE(PG8_SA(0, 1), cA + hstepA, voffA);
;         if (wr == 1) PG8_BAR;
;         PG8_WAIT_V(2); PG8_BAR;
;         PG8_STAGE(PG8_SB(1, 0), cB + kstep, voffB); PG8_STAGE(PG8_SA(1, 0), cA + kstep, voffA); PG8_STAGE(PG8_SB(1, 1), cB + hstepB + kstep, voffB);
;         PG8_WAIT_V(6); PG8_BAR;
;     ...
;         if constexpr (Epi::NEEDS_RS) { if (wid < 4) __builtin_amdgcn_global_load_lds((const unsigned*)(E.rsv + cur.pm * 256 + wid * 64 + lane), (LAS unsigned*)(lds + rsoff + wid * 256), 4, 0, 0); }
.LBB0_330:
	s_mov_b64 s[14:15], 0x80
	s_add_i32 m0, s25, 0x18000
	v_lshl_add_u64 v[0:1], v[0:1], 0, s[14:15]
	global_load_lds_dwordx4 v[0:1], off
	v_lshl_add_u64 v[0:1], v[2:3], 0, s[14:15]
	s_add_i32 m0, s25, 0x1a000
	s_add_i32 s42, s25, 0x8000
	global_load_lds_dwordx4 v[0:1], off
	v_lshl_add_u64 v[0:1], v[8:9], 0, s[14:15]
	s_mov_b32 m0, s42
	s_add_i32 s43, s25, 0xa000
	global_load_lds_dwordx4 v[0:1], off
	v_lshl_add_u64 v[0:1], v[10:11], 0, s[14:15]
	s_mov_b32 m0, s43
	s_sext_i32_i8 s50, s6
	global_load_lds_dwordx4 v[0:1], off
	s_add_i32 m0, s25, 0x1c000
	v_lshl_add_u64 v[0:1], v[4:5], 0, s[14:15]
	global_load_lds_dwordx4 v[0:1], off
	v_lshl_add_u64 v[0:1], v[6:7], 0, s[14:15]
	s_add_i32 m0, s25, 0x1e000
	v_and_b32_e32 v2, 15, v12
	global_load_lds_dwordx4 v[0:1], off
	s_waitcnt vmcnt(8)
	s_barrier
	v_lshrrev_b32_e32 v0, 1, v12
	v_and_b32_e32 v0, 24, v0
	s_lshr_b32 s6, s9, 26
	v_lshlrev_b32_e32 v3, 1, v0
	s_add_i32 s6, s8, s6
	v_lshl_or_b32 v142, s12, 6, v2
	v_lshl_or_b32 v3, v2, 6, v3
	v_lshlrev_b32_e32 v2, 2, v2
	s_ashr_i32 s44, s6, 6
	s_lshl_b32 s6, s12, 13
	v_and_b32_e32 v4, 32, v2
	v_bitop3_b32 v5, v3, s6, v4 bitop3:0xde
	s_lshl_b32 s6, s11, 5
	s_and_b32 s16, s6, 0x60
	s_lshl_b32 s6, s16, 7
	s_cmp_lt_i32 s11, 4
	v_bitop3_b32 v143, v3, s6, v4 bitop3:0xde
	s_cselect_b64 s[6:7], -1, 0
	s_cmp_gt_i32 s8, 63
	s_cselect_b64 s[8:9], -1, 0
	s_lshl_b32 s12, s12, 8
	s_add_i32 s12, s12, 0
	v_add_u32_e32 v156, s12, v2
	s_and_b32 s12, s10, 0xffffffc0
	s_ashr_i32 s13, s12, 31
	s_lshl_b64 s[12:13], s[12:13], 2
	v_readlane_b32 s14, v254, 25
	v_and_b32_e32 v1, 63, v12
	v_readlane_b32 s15, v254, 26
	s_add_u32 s12, s14, s12
	s_addc_u32 s13, s15, s13
	v_lshlrev_b32_e32 v146, 2, v1
	v_lshlrev_b32_e32 v1, 14, v13
	v_lshl_add_u64 v[2:3], s[12:13], 0, v[146:147]
	s_mov_b64 s[12:13], 0x1e848000
	v_and_b32_e32 v1, 0xffff8000, v1
	v_lshl_add_u64 v[136:137], v[2:3], 0, s[12:13]
	v_lshl_add_u32 v1, v14, 11, v1
	v_and_b32_e32 v2, 1, v13
	v_lshl_or_b32 v1, v2, 6, v1
	v_lshl_add_u32 v138, v15, 1, v1
	v_lshlrev_b32_e32 v1, 14, v16
	s_lshl_b32 s11, s11, 8
	v_and_b32_e32 v1, 0xffff8000, v1
	s_waitcnt vmcnt(6)
	s_add_i32 s45, s11, 0
	s_add_i32 s46, s44, -2
	v_lshl_add_u32 v1, v17, 11, v1
	v_and_b32_e32 v2, 1, v16
	s_cmpk_lt_u32 s10, 0x100
	v_lshl_or_b32 v1, v2, 6, v1
	s_cselect_b64 s[14:15], -1, 0
	s_ashr_i32 s47, s34, 31
	v_mov_b32_e32 v139, v147
	v_lshl_add_u32 v140, v18, 1, v1
	v_mov_b32_e32 v141, v147
	s_mov_b32 s17, 0
	v_add_u32_e32 v157, 0, v5
	s_lshl_b32 s68, s16, 1
	v_lshlrev_b32_e32 v146, 1, v0
	s_barrier
	s_branch .LBB0_333

; #define LAS __attribute__((address_space(3)))
; #define PG8_STAGE(bufoff, gbase, voff) do { _Pragma("unroll") for (int _i = 0; _i < 2; ++_i) \
;         __builtin_amdgcn_global_load_lds((const unsigned*)((const char*)(gbase) + (voff)[_i]), (LAS unsigned*)(lds + (bufoff) + ldsw + _i * 8192), 16, 0, 0); } while (0)
; #define PG8_WAIT_V(n) asm volatile("s_waitcnt vmcnt(" #n ")" ::: "memory")
; #define PG8_BAR __builtin_amdgcn_s_barrier()
;     ...
;     for (int i = 0; i < 2; ++i) { int R, C; stage_rc(tid * 16 + i * 8192, R, C); const int Rb = Epi::PERM ? ((R & ~31) + perm32(R & 31)) : R;
;         voffA[i] = (unsigned)(R * g.lda + C) * 2u; voffB[i] = (unsigned)(Rb * K + C) * 2u; }
;     const size_t kstep = (size_t)(BK * 2);
;     const size_t hstepA = (size_t)HALF * g.lda * 2, hstepB = (size_t)HALF * K * 2;
;     const size_t tstepA = 2 * hstepA, tstepB = 2 * hstepB;
;     const unsigned ldsw = (unsigned)wid * 1024u;
;     const int aoff = lds_byte(wr * 64 + fr, fq * 8), boff = lds_byte(wc * 32 + fr, fq * 8);
;     ...
;         PG8_STAGE(PG8_SB(0, 0), cB, voffB); PG8_STAGE(PG8_SB(0, 1), cB + hstepB, voffB); PG8_STAGE(PG8_SA(0, 0), cA, voffA); PG8_STAGE(PG8_SA(0, 1), cA + hstepA, voffA);
;         if (wr == 1) PG8_BAR;
;         PG8_WAIT_V(2); PG8_BAR;
;         PG8_STAGE(PG8_SB(1, 0), cB + kstep, voffB); PG8_STAGE(PG8_SA(1, 0), cA + kstep, voffA); PG8_STAGE(PG8_SB(1, 1), cB + hstepB + kstep, voffB);
;         PG8_WAIT_V(6); PG8_BAR;
;     ...
;         if constexpr (Epi::NEEDS_RS) { if (wid < 4) __builtin_amdgcn_global_load_lds((const unsigned*)(E.rsv + cur.pm * 256 + wid * 64 + lane), (LAS unsigned*)(lds + rsoff + wid * 256), 4, 0, 0); }
.LBB0_542:
	s_mov_b64 s[6:7], 0x80
	s_add_i32 m0, s36, 0x18000
	v_lshl_add_u64 v[8:9], v[8:9], 0, s[6:7]
	global_load_lds_dwordx4 v[8:9], off
	v_lshl_add_u64 v[4:5], v[4:5], 0, s[6:7]
	s_add_i32 m0, s36, 0x1a000
	s_add_i32 s40, s36, 0x8000
	global_load_lds_dwordx4 v[4:5], off
	v_lshl_add_u64 v[4:5], v[6:7], 0, s[6:7]
	s_mov_b32 m0, s40
	s_add_i32 s41, s36, 0xa000
	global_load_lds_dwordx4 v[4:5], off
	v_lshl_add_u64 v[4:5], v[10:11], 0, s[6:7]
	s_mov_b32 m0, s41
	v_lshl_add_u64 v[2:3], v[2:3], 0, s[6:7]
	global_load_lds_dwordx4 v[4:5], off
	s_add_i32 m0, s36, 0x1c000
	v_lshl_add_u64 v[0:1], v[0:1], 0, s[6:7]
	global_load_lds_dwordx4 v[2:3], off
	s_add_i32 m0, s36, 0x1e000
	v_lshrrev_b32_e32 v2, 1, v12
	global_load_lds_dwordx4 v[0:1], off
	s_waitcnt vmcnt(8)
	s_barrier
	v_and_b32_e32 v1, 15, v12
	s_lshr_b32 s6, s9, 26
	v_and_b32_e32 v136, 24, v2
	v_and_b32_e32 v2, 48, v12
	s_add_i32 s6, s8, s6
	v_lshl_or_b32 v137, s12, 6, v1
	v_lshl_or_b32 v2, v1, 6, v2
	v_lshlrev_b32_e32 v1, 2, v1
	s_and_b32 s18, s11, 3
	s_ashr_i32 s42, s6, 6
	s_lshl_b32 s6, s12, 13
	v_and_b32_e32 v3, 32, v1
	v_bitop3_b32 v4, v2, s6, v3 bitop3:0xde
	s_lshl_b32 s43, s18, 5
	s_lshl_b32 s6, s18, 12
	s_cmp_lt_i32 s11, 4
	v_bitop3_b32 v161, v2, s6, v3 bitop3:0xde
	s_cselect_b64 s[6:7], -1, 0
	s_cmp_gt_i32 s8, 63
	s_cselect_b64 s[8:9], -1, 0
	s_lshl_b32 s12, s12, 8
	s_add_i32 s12, s12, 0
	v_add_u32_e32 v162, s12, v1
	s_and_b32 s12, s10, 0xffffffc0
	s_lshl_b32 s11, s11, 8
	s_ashr_i32 s13, s12, 31
	s_add_i32 s44, s11, 0
	s_add_i32 s45, s42, -2
	s_cmpk_lt_u32 s10, 0x100
	s_cselect_b64 s[16:17], -1, 0
	s_cmp_eq_u32 s18, 0
	s_cselect_b64 s[18:19], -1, 0
	s_ashr_i32 s46, s31, 31
	s_ashr_i32 s47, s34, 31
	s_lshl_b64 s[10:11], s[12:13], 2
	v_readlane_b32 s12, v254, 25
	v_and_b32_e32 v0, 63, v12
	v_readlane_b32 s13, v254, 26
	s_add_u32 s10, s12, s10
	v_and_b32_e32 v2, 32, v12
	s_addc_u32 s11, s13, s11
	v_lshlrev_b32_e32 v146, 2, v0
	v_lshl_add_u64 v[0:1], s[10:11], 0, v[146:147]
	s_mov_b64 s[10:11], 0x1e848000
	v_lshlrev_b32_e32 v146, 1, v2
	v_lshl_add_u64 v[138:139], v[0:1], 0, s[10:11]
	v_lshl_add_u64 v[0:1], s[12:13], 0, v[146:147]
	v_and_b32_e32 v146, 16, v12
	v_lshl_add_u64 v[0:1], v[0:1], 0, v[146:147]
	s_mov_b64 s[10:11], 0x16200000
	v_lshl_add_u64 v[140:141], v[0:1], 0, s[10:11]
	v_lshlrev_b32_e32 v0, 14, v13
	v_and_b32_e32 v0, 0xffff8000, v0
	v_lshl_add_u32 v0, v14, 11, v0
	v_and_b32_e32 v1, 1, v13
	v_lshl_or_b32 v0, v1, 6, v0
	v_lshl_add_u32 v142, v15, 1, v0
	v_lshlrev_b32_e32 v0, 14, v16
	v_and_b32_e32 v0, 0xffff8000, v0
	s_waitcnt vmcnt(6)
	v_lshl_add_u32 v0, v17, 11, v0
	v_and_b32_e32 v1, 1, v16
	v_lshl_or_b32 v0, v1, 6, v0
	s_mov_b32 s15, 0
	v_mov_b32_e32 v143, v147
	v_lshl_add_u32 v156, v18, 1, v0
	v_mov_b32_e32 v157, v147
	v_add_u32_e32 v163, 0, v4
	s_barrier
	s_branch .LBB0_545
